# MLA head prologue: redundant third barrier removed (the loop's first barrier follows immediately and buffer 0 is no longer re-stored); MLA inner-loop header aligned to 64 bytes
# baseline (speedup 1.0000x reference)
; DI int tid() { int t = threadIdx.x; asm volatile("" : "+v"(t)); return t; }
; #define M2_STORE(S, buf) { M2_SK(0, S##k0, buf) M2_SK(1, S##k1, buf) M2_SK(2, S##k2, buf) M2_SV(0, S##v0, buf) M2_SV(1, S##v1, buf) }
; DI void flash_mla2(const bf16_t* __restrict__ Qp, const bf16_t* __restrict__ Kp, const bf16_t* __restrict__ Vtp,
;                    bf16_t* __restrict__ Op, char* smem, float& ssq) {
;     ...
;     const int t = tid(), lane = t & 63, w = __builtin_amdgcn_readfirstlane(t >> 6), l32 = lane & 31, h = lane >> 5;
;     const int q = w * 32 + l32;
;     const unsigned ktoff = (unsigned)(t * 8);
;     const unsigned vtoff = (unsigned)((t >> 3) * LDV + (t & 7) * 8);
;     bf16x8 qf[NKS];
; #pragma unroll
;     for (int ks = 0; ks < NKS; ++ks) qf[ks] = *(const bf16x8*)(Qp + (size_t)q * LDQ + ks * 16 + 8 * h);
;     f32x16 o[NMT];
; #pragma unroll
;     for (int mt = 0; mt < NMT; ++mt)
; #pragma unroll
;         for (int r = 0; r < 16; ++r) o[mt][r] = 0.f;
;     float m = 0.f, lsum = 0.f;
;     uint4 ak0, ak1, ak2, av0, av1, bk0, bk1, bk2, bv0, bv1;
;     ...
;     float alpha = 1.f;
;     __syncthreads();
;     M2_LOAD(a, 0);
;     M2_LOAD(b, 1);
;     {
;         M2_STORE(a, 0);
;         __syncthreads();
.LBB0_182:
	s_add_i32 s18, s34, s13
	s_ashr_i32 s19, s18, 31
	s_lshl_b64 s[16:17], s[18:19], 13
	s_or_b32 s16, s16, s12
	s_mulk_i32 s17, 0xc0
	s_mul_hi_u32 s35, s16, 0xc0
	s_add_i32 s35, s35, s17
	s_mulk_i32 s16, 0xc0
	s_add_u32 s36, s6, s16
	s_addc_u32 s37, s7, s35
	s_mul_i32 s16, s18, 0x180000
	s_mul_hi_i32 s17, s18, 0x180000
	s_add_u32 s16, s8, s16
	s_addc_u32 s17, s9, s17
	s_lshl_b64 s[18:19], s[18:19], 20
	v_mov_b32_e32 v1, v182
	s_add_u32 s18, s10, s18
	s_addc_u32 s19, s11, s19
	v_readfirstlane_b32 s35, v1
	s_ashr_i32 s35, s35, 1
	s_waitcnt vmcnt(1)
	v_bfe_u32 v142, v1, 5, 1
	v_mov_b32_e32 v2, s35
	v_bfi_b32 v132, s80, v2, v1
	v_mov_b64_e32 v[2:3], s[36:37]
	v_mad_i64_i32 v[2:3], s[36:37], v132, s86, v[2:3]
	v_lshlrev_b32_e32 v4, 4, v142
	v_mov_b32_e32 v5, v35
	v_lshlrev_b32_e32 v34, 3, v1
	v_lshl_add_u64 v[2:3], v[2:3], 0, v[4:5]
	global_load_dwordx4 v[68:71], v[2:3], off
	global_load_dwordx4 v[72:75], v[2:3], off offset:32
	global_load_dwordx4 v[76:79], v[2:3], off offset:64
	global_load_dwordx4 v[80:83], v[2:3], off offset:96
	global_load_dwordx4 v[84:87], v[2:3], off offset:128
	global_load_dwordx4 v[88:91], v[2:3], off offset:160
	v_lshl_add_u64 v[2:3], v[34:35], 1, s[16:17]
	v_add_co_u32_e32 v6, vcc, s84, v2
	v_ashrrev_i32_e32 v5, 3, v1
	v_and_b32_e32 v12, 56, v34
	v_addc_co_u32_e32 v7, vcc, 0, v3, vcc
	v_lshl_or_b32 v134, v5, 6, v12
	v_mov_b32_e32 v135, v35
	s_barrier
	global_load_dwordx4 v[92:95], v[2:3], off
	global_load_dwordx4 v[100:103], v[6:7], off offset:-4096
	global_load_dwordx4 v[96:99], v[6:7], off
	v_lshl_add_u64 v[6:7], v[134:135], 1, s[18:19]
	s_mov_b32 s35, 0x1000
	v_add_co_u32_e32 v8, vcc, s35, v6
	global_load_dwordx4 v[104:107], v[6:7], off
	s_nop 0
	v_addc_co_u32_e32 v9, vcc, 0, v7, vcc
	global_load_dwordx4 v[108:111], v[8:9], off
	v_mul_hi_i32 v10, v1, s87
	v_add_u32_e32 v13, 0x100, v1
	v_lshrrev_b32_e32 v11, 31, v10
	v_ashrrev_i32_e32 v10, 1, v10
	v_mul_hi_i32 v14, v13, s87
	v_add_u32_e32 v10, v10, v11
	v_lshrrev_b32_e32 v11, 31, v14
	v_ashrrev_i32_e32 v14, 1, v14
	v_mul_lo_u32 v15, v10, -12
	v_and_b32_e32 v16, 0xffffff3, v10
	v_lshlrev_b32_e32 v17, 1, v10
	v_lshrrev_b32_e32 v10, 1, v10
	v_add_u32_e32 v14, v14, v11
	v_and_b32_e32 v11, 8, v17
	v_and_b32_e32 v10, 4, v10
	v_or3_b32 v10, v11, v16, v10
	v_add_lshl_u32 v15, v15, v1, 4
	v_mul_lo_u32 v10, v10, s88
	s_movk_i32 s35, 0x4000
	s_waitcnt vmcnt(11)
	v_add3_u32 v144, 0, v10, v15
	v_add_co_u32_e32 v10, vcc, s35, v2
	v_lshlrev_b32_e32 v19, 1, v14
	s_nop 0
	v_addc_co_u32_e32 v11, vcc, 0, v3, vcc
	v_add_co_u32_e32 v2, vcc, s83, v2
	v_and_b32_e32 v18, 0xffffff3, v14
	s_nop 0
	v_addc_co_u32_e32 v3, vcc, 0, v3, vcc
	v_add_co_u32_e32 v6, vcc, 0x2000, v6
	s_nop 1
	v_addc_co_u32_e32 v7, vcc, 0, v7, vcc
	v_add_co_u32_e32 v8, vcc, 0x2000, v8
	s_nop 1
	v_addc_co_u32_e32 v9, vcc, 0, v9, vcc
	global_load_dwordx4 v[112:115], v[10:11], off offset:-4096
	global_load_dwordx4 v[116:119], v[10:11], off
	global_load_dwordx4 v[120:123], v[6:7], off
	global_load_dwordx4 v[124:127], v[2:3], off
	global_load_dwordx4 v[128:131], v[8:9], off
	v_lshrrev_b32_e32 v2, 1, v14
	v_and_b32_e32 v16, 8, v19
	v_and_b32_e32 v2, 4, v2
	v_mul_lo_u32 v17, v14, -12
	v_or3_b32 v2, v16, v18, v2
	v_and_b32_e32 v44, 31, v1
	v_mul_lo_u32 v2, v2, s88
	v_add_lshl_u32 v3, v17, v13, 4
	v_add_u32_e32 v1, 0x200, v1
	v_add3_u32 v145, 0, v2, v3
	v_mul_hi_i32 v2, v1, s87
	v_lshrrev_b32_e32 v3, 31, v2
	v_ashrrev_i32_e32 v2, 1, v2
	v_add_u32_e32 v2, v2, v3
	v_mul_lo_u32 v3, v2, -12
	v_and_b32_e32 v6, 0xffffff3, v2
	v_lshlrev_b32_e32 v7, 1, v2
	v_lshrrev_b32_e32 v2, 1, v2
	v_and_b32_e32 v7, 8, v7
	v_and_b32_e32 v2, 4, v2
	v_or3_b32 v2, v7, v6, v2
	v_mul_lo_u32 v2, v2, s88
	v_add_lshl_u32 v1, v3, v1, 4
	v_add3_u32 v146, 0, v2, v1
	v_mul_lo_u32 v1, v5, s81
	v_lshlrev_b32_e32 v2, 1, v12
	v_add3_u32 v147, 0, v1, v2
	v_lshrrev_b32_e32 v1, 3, v13
	v_mul_lo_u32 v1, v1, s81
	v_add3_u32 v148, 0, v1, v2
	v_mul_u32_u24_e32 v1, 0x68, v44
	v_lshlrev_b32_e32 v1, 1, v1
	v_add3_u32 v149, 0, v1, v4
	v_ashrrev_i32_e32 v133, 31, v132
	v_mov_b32_e32 v138, 1.0
	s_mov_b32 s35, -2
	v_mov_b32_e32 v140, 0
	s_waitcnt vmcnt(9)
	ds_write_b128 v144, v[92:95]
	s_waitcnt vmcnt(8)
	ds_write_b128 v145, v[100:103]
	s_waitcnt vmcnt(7)
	ds_write_b128 v146, v[96:99]
	s_waitcnt vmcnt(6)
	ds_write_b128 v147, v[104:107] offset:26624
	s_waitcnt vmcnt(5)
	ds_write_b128 v148, v[108:111] offset:26624
	s_add_u32 s36, s16, 0x6000
	s_addc_u32 s37, s17, 0
	s_mov_b32 s41, 2
	v_lshl_add_u64 v[36:37], v[34:35], 1, s[36:37]
	s_lshl_b32 s36, s41, 13
	global_load_dwordx4 v[92:95], v[36:37], off
	v_add_co_u32_e32 v36, vcc, s84, v36
	s_add_u32 s36, s18, s36
	s_nop 0
	v_addc_co_u32_e32 v37, vcc, 0, v37, vcc
	s_addc_u32 s37, s19, 0
	global_load_dwordx4 v[100:103], v[36:37], off offset:-4096
	global_load_dwordx4 v[96:99], v[36:37], off
	v_lshl_add_u64 v[36:37], v[134:135], 1, s[36:37]
	global_load_dwordx4 v[104:107], v[36:37], off
	v_add_co_u32_e32 v36, vcc, 0x1000, v36
	s_nop 1
	v_addc_co_u32_e32 v37, vcc, 0, v37, vcc
	global_load_dwordx4 v[108:111], v[36:37], off
	s_waitcnt lgkmcnt(0)
	s_barrier
; #define MFMA(a, b, c) __builtin_amdgcn_mfma_f32_32x32x16_bf16((a), (b), (c), 0, 0, 0)
; DI void flash_mla2(const bf16_t* __restrict__ Qp, const bf16_t* __restrict__ Kp, const bf16_t* __restrict__ Vtp,
;                    bf16_t* __restrict__ Op, char* smem, float& ssq) {
;     ...
;         const bf16_t* kb = Ks + l32 * KP + 8 * h;
;         f32x16 s0, s1;
; #pragma unroll
;         for (int r = 0; r < 16; ++r) { s0[r] = 0.f; s1[r] = 0.f; }
; #pragma unroll
;         for (int ks = 0; ks < NKS; ++ks) { bf16x8 k0 = *(const bf16x8*)(kb + ks * 16); bf16x8 k1 = *(const bf16x8*)(kb + 32 * KP + ks * 16); s0 = MFMA(k0, qf[ks], s0); s1 = MFMA(k1, qf[ks], s1); }
;         float mx = s0[0];
; #pragma unroll
;         for (int r = 1; r < 16; ++r) mx = fmaxf(mx, s0[r]);
; #pragma unroll
;         for (int r = 0; r < 16; ++r) mx = fmaxf(mx, s1[r]);
;         m = fmaxf(mx, __shfl_xor(mx, 32));
;         __syncthreads();
	ds_read_b128 v[2:5], v149
	ds_read_b128 v[18:21], v149 offset:32
	s_waitcnt lgkmcnt(1)
	v_mfma_f32_32x32x16_bf16 v[2:17], v[2:5], v[68:71], 0
	s_waitcnt lgkmcnt(0)
	v_mfma_f32_32x32x16_bf16 v[2:17], v[18:21], v[72:75], v[2:17]
	ds_read_b128 v[18:21], v149 offset:64
	ds_read_b128 v[22:25], v149 offset:96
	s_waitcnt lgkmcnt(1)
	v_mfma_f32_32x32x16_bf16 v[2:17], v[18:21], v[76:79], v[2:17]
	s_waitcnt lgkmcnt(0)
	v_mfma_f32_32x32x16_bf16 v[2:17], v[22:25], v[80:83], v[2:17]
	ds_read_b128 v[18:21], v149 offset:128
	ds_read_b128 v[22:25], v149 offset:160
	s_waitcnt lgkmcnt(1)
	v_mfma_f32_32x32x16_bf16 v[2:17], v[18:21], v[84:87], v[2:17]
	ds_read_b128 v[18:21], v149 offset:6656
	ds_read_b128 v[36:39], v149 offset:6688
	s_waitcnt lgkmcnt(2)
	v_mfma_f32_32x32x16_bf16 v[2:17], v[22:25], v[88:91], v[2:17]
	s_waitcnt lgkmcnt(1)
	v_mfma_f32_32x32x16_bf16 v[18:33], v[18:21], v[68:71], 0
	s_nop 9
	v_max_f32_e32 v1, v3, v3
	v_max_f32_e32 v2, v2, v2
	v_max_f32_e32 v1, v2, v1
	v_max3_f32 v1, v1, v4, v5
	v_max3_f32 v1, v1, v6, v7
	v_max3_f32 v1, v1, v8, v9
	v_max3_f32 v1, v1, v10, v11
	s_waitcnt lgkmcnt(0)
	v_mfma_f32_32x32x16_bf16 v[18:33], v[36:39], v[72:75], v[18:33]
	ds_read_b128 v[36:39], v149 offset:6720
	ds_read_b128 v[40:43], v149 offset:6752
	v_max3_f32 v1, v1, v12, v13
	v_max3_f32 v1, v1, v14, v15
	v_max3_f32 v1, v1, v16, v17
	v_xor_b32_e32 v2, 32, v184
	v_cmp_lt_i32_e32 vcc, v2, v187
	v_mov_b32_e32 v3, v0
	s_waitcnt lgkmcnt(1)
	v_mfma_f32_32x32x16_bf16 v[18:33], v[36:39], v[76:79], v[18:33]
	v_cndmask_b32_e32 v2, v184, v2, vcc
	v_lshlrev_b32_e32 v143, 2, v2
	v_mov_b32_e32 v4, v0
	v_mov_b32_e32 v5, v0
	v_mov_b32_e32 v6, v0
	v_mov_b32_e32 v7, v0
	v_mov_b32_e32 v8, v0
	s_waitcnt lgkmcnt(0)
	v_mfma_f32_32x32x16_bf16 v[18:33], v[40:43], v[80:83], v[18:33]
	ds_read_b128 v[36:39], v149 offset:6784
	ds_read_b128 v[40:43], v149 offset:6816
	v_mov_b32_e32 v9, v0
	v_mov_b32_e32 v10, v0
	v_mov_b32_e32 v11, v0
	v_mov_b32_e32 v12, v0
	v_mov_b32_e32 v13, v0
	v_mov_b32_e32 v14, v0
	s_waitcnt lgkmcnt(1)
	v_mfma_f32_32x32x16_bf16 v[18:33], v[36:39], v[84:87], v[18:33]
	v_mov_b32_e32 v15, v0
	v_mov_b32_e32 v16, v0
	v_mov_b32_e32 v17, v0
	s_waitcnt lgkmcnt(0)
	v_mfma_f32_32x32x16_bf16 v[18:33], v[40:43], v[88:91], v[18:33]
	s_nop 11
	v_max3_f32 v1, v1, v18, v19
	v_max3_f32 v1, v1, v20, v21
	v_max3_f32 v1, v1, v22, v23
	v_max3_f32 v1, v1, v24, v25
	v_max3_f32 v1, v1, v26, v27
	v_max3_f32 v1, v1, v28, v29
	v_max3_f32 v1, v1, v30, v31
	v_max3_f32 v1, v1, v32, v33
	ds_bpermute_b32 v2, v143, v1
	v_mov_b32_e32 v18, v0
	v_mov_b32_e32 v19, v0
	v_mov_b32_e32 v20, v0
	v_mov_b32_e32 v21, v0
	s_waitcnt lgkmcnt(0)
	v_max_f32_e32 v2, v2, v2
	v_max_f32_e32 v141, v1, v2
	v_lshlrev_b32_e32 v1, 6, v44
	v_mov_b32_e32 v2, v0
	v_mov_b32_e32 v22, v0
	v_mov_b32_e32 v23, v0
	v_mov_b32_e32 v24, v0
	v_mov_b32_e32 v25, v0
	v_mov_b32_e32 v26, v0
	v_mov_b32_e32 v27, v0
	v_mov_b32_e32 v28, v0
	v_mov_b32_e32 v29, v0
	v_mov_b32_e32 v30, v0
	v_mov_b32_e32 v31, v0
	v_sub_u32_e32 v150, v149, v1
	v_mov_b32_e32 v1, v0
	v_mov_b64_e32 v[32:33], v[30:31]
	v_mov_b64_e32 v[30:31], v[28:29]
	v_mov_b64_e32 v[28:29], v[26:27]
	v_mov_b64_e32 v[26:27], v[24:25]
	v_mov_b64_e32 v[24:25], v[22:23]
	v_mov_b64_e32 v[22:23], v[20:21]
	v_mov_b64_e32 v[20:21], v[18:19]
	v_mov_b64_e32 v[18:19], v[16:17]
	v_mov_b64_e32 v[16:17], v[14:15]
	v_mov_b64_e32 v[14:15], v[12:13]
	v_mov_b64_e32 v[12:13], v[10:11]
	v_mov_b64_e32 v[10:11], v[8:9]
	v_mov_b64_e32 v[8:9], v[6:7]
	v_mov_b64_e32 v[6:7], v[4:5]
	v_mov_b64_e32 v[4:5], v[2:3]
	v_mov_b64_e32 v[2:3], v[0:1]
	v_lshlrev_b32_e32 v136, 1, v34
	v_lshlrev_b32_e32 v151, 1, v134
	v_add_u32_e32 v137, 0x2000, v136
	v_xor_b32_e32 v179, 0x80000000, v141
	v_mov_b32_e32 v232, v179
	v_mov_b32_e32 v233, v179
	v_mov_b32_e32 v234, v179
	v_mov_b32_e32 v235, v179
	v_mov_b32_e32 v236, v179
	v_mov_b32_e32 v237, v179
	v_mov_b32_e32 v238, v179
	v_mov_b32_e32 v239, v179
	v_mov_b32_e32 v240, v179
	v_mov_b32_e32 v241, v179
	v_mov_b32_e32 v242, v179
	v_mov_b32_e32 v243, v179
	v_mov_b32_e32 v244, v179
	v_mov_b32_e32 v245, v179
	v_mov_b32_e32 v246, v179
	v_mov_b32_e32 v247, v179
	s_branch .LBB0_184
	.p2align 6
